# S8 context-row tile: triple-buffered batched fragment loads (11 k-steps)
# baseline (speedup 1.0000x reference)
; #define LAS __attribute__((address_space(3)))
; template <int CH>
; DEV void cg_chunk(f32x4 (&acc)[4][4], const bf16_t* ap, const bf16_t* bp, const int (&brow)[4], int K) {
;     bf16x8 a[CH][4], b[CH][4];
; #pragma unroll
;     for (int c = 0; c < CH; ++c)
; #pragma unroll
;         for (int i = 0; i < 4; ++i) { a[c][i] = *(const bf16x8*)(ap + (size_t)(16 * i) * K + 32 * c); b[c][i] = *(const bf16x8*)(bp + (size_t)brow[i] * K + 32 * c); }
; #pragma unroll
;     for (int c = 0; c < CH; ++c)
; #pragma unroll
;         for (int mi = 0; mi < 4; ++mi)
; #pragma unroll
;             for (int ni = 0; ni < 4; ++ni) acc[mi][ni] = __builtin_amdgcn_mfma_f32_16x16x32_bf16(b[c][ni], a[c][mi], acc[mi][ni], 0, 0, 0);
; }
; template <int MODE>
; DEV void cgemm_tile(const Fr& F, const bf16_t* A, const bf16_t* Bt, int K, int rb, int cb, bf16_t* O, int ldc) {
;     LAS float* part = (LAS float*)F.lds;
;     const int w = F.wave, fr = F.lane & 15, fq = F.lane >> 4;
;     const int arow0 = (rb >> 2) * RPB + (rb & 3) * 64;
;     int brow[4];
; #pragma unroll
;     for (int ni = 0; ni < 4; ++ni) {
;         if (MODE == 0) brow[ni] = cb * 64 + ni * 16;
;         else { const int j = cb * 32 + (ni & 1) * 16; brow[ni] = (j >> 7) * 256 + (ni >> 1) * 128 + (j & 127); }
;     }
;     const int kslice = K >> 3, steps = kslice >> 5;
;     const bf16_t* ap = A + (size_t)(arow0 + fr) * K + w * kslice + 8 * fq;
;     const bf16_t* bp = Bt + (size_t)fr * K + w * kslice + 8 * fq;
;     f32x4 acc[4][4];
; #pragma unroll
;     for (int mi = 0; mi < 4; ++mi)
; #pragma unroll
;         for (int ni = 0; ni < 4; ++ni) acc[mi][ni] = (f32x4){0.f, 0.f, 0.f, 0.f};
;     int s = 0;
;     for (; s + 4 <= steps; s += 4) cg_chunk<4>(acc, ap + s * 32, bp + s * 32, brow, K);
;     if (steps - s == 3) cg_chunk<3>(acc, ap + s * 32, bp + s * 32, brow, K);
;     else if (steps - s == 2) cg_chunk<2>(acc, ap + s * 32, bp + s * 32, brow, K);
;     else if (steps - s == 1) cg_chunk<1>(acc, ap + s * 32, bp + s * 32, brow, K);
.LBB0_1385:
	s_add_i32 s1, s0, 16
	s_add_i32 s3, s0, 32
	s_add_i32 s18, s0, 48
	v_mad_i64_i32 v[86:87], s[6:7], s1, v197, v[92:93]
	v_mad_i64_i32 v[174:175], s[6:7], s3, v197, v[92:93]
	v_mad_i64_i32 v[172:173], s[6:7], s18, v197, v[92:93]
	v_mad_i64_i32 v[78:79], s[6:7], s0, v197, v[92:93]
	s_ashr_i32 s1, s0, 31
	s_add_i32 s2, s2, 32
	global_load_dwordx4 v[66:69], v[78:79], off
	global_load_dwordx4 v[70:73], v[86:87], off
	global_load_dwordx4 v[80:83], v[174:175], off
	global_load_dwordx4 v[100:103], v[172:173], off
	global_load_dwordx4 v[104:107], v[90:91], off
	global_load_dwordx4 v[108:111], v[94:95], off
	global_load_dwordx4 v[112:115], v[96:97], off
	global_load_dwordx4 v[116:119], v[98:99], off
	global_load_dwordx4 v[120:123], v[78:79], off offset:64
	global_load_dwordx4 v[124:127], v[86:87], off offset:64
	global_load_dwordx4 v[128:131], v[174:175], off offset:64
	global_load_dwordx4 v[132:135], v[172:173], off offset:64
	global_load_dwordx4 v[136:139], v[90:91], off offset:64
	global_load_dwordx4 v[152:155], v[94:95], off offset:64
	global_load_dwordx4 v[156:159], v[96:97], off offset:64
	global_load_dwordx4 v[160:163], v[98:99], off offset:64
	global_load_dwordx4 v[164:167], v[78:79], off offset:128
	global_load_dwordx4 v[200:203], v[86:87], off offset:128
	global_load_dwordx4 v[204:207], v[174:175], off offset:128
	global_load_dwordx4 v[208:211], v[172:173], off offset:128
	global_load_dwordx4 v[212:215], v[90:91], off offset:128
	global_load_dwordx4 v[216:219], v[94:95], off offset:128
	global_load_dwordx4 v[220:223], v[96:97], off offset:128
	global_load_dwordx4 v[224:227], v[98:99], off offset:128
	s_waitcnt vmcnt(16)
	v_mfma_f32_16x16x32_bf16 v[2:5], v[66:69], v[104:107], 0
	v_mfma_f32_16x16x32_bf16 v[6:9], v[70:73], v[104:107], 0
	v_mfma_f32_16x16x32_bf16 v[10:13], v[80:83], v[104:107], 0
	v_mfma_f32_16x16x32_bf16 v[14:17], v[100:103], v[104:107], 0
	v_mfma_f32_16x16x32_bf16 v[18:21], v[66:69], v[108:111], 0
	v_mfma_f32_16x16x32_bf16 v[22:25], v[70:73], v[108:111], 0
	v_mfma_f32_16x16x32_bf16 v[26:29], v[80:83], v[108:111], 0
	v_mfma_f32_16x16x32_bf16 v[30:33], v[100:103], v[108:111], 0
	v_mfma_f32_16x16x32_bf16 v[34:37], v[66:69], v[112:115], 0
	v_mfma_f32_16x16x32_bf16 v[38:41], v[70:73], v[112:115], 0
	v_mfma_f32_16x16x32_bf16 v[42:45], v[80:83], v[112:115], 0
	v_mfma_f32_16x16x32_bf16 v[46:49], v[100:103], v[112:115], 0
	v_mfma_f32_16x16x32_bf16 v[50:53], v[66:69], v[116:119], 0
	v_mfma_f32_16x16x32_bf16 v[54:57], v[70:73], v[116:119], 0
	v_mfma_f32_16x16x32_bf16 v[58:61], v[80:83], v[116:119], 0
	v_mfma_f32_16x16x32_bf16 v[62:65], v[100:103], v[116:119], 0
	global_load_dwordx4 v[66:69], v[78:79], off offset:192
	global_load_dwordx4 v[70:73], v[86:87], off offset:192
	global_load_dwordx4 v[80:83], v[174:175], off offset:192
	global_load_dwordx4 v[100:103], v[172:173], off offset:192
	global_load_dwordx4 v[104:107], v[90:91], off offset:192
	global_load_dwordx4 v[108:111], v[94:95], off offset:192
	global_load_dwordx4 v[112:115], v[96:97], off offset:192
	global_load_dwordx4 v[116:119], v[98:99], off offset:192
	s_waitcnt vmcnt(16)
	v_mfma_f32_16x16x32_bf16 v[2:5], v[120:123], v[136:139], v[2:5]
	v_mfma_f32_16x16x32_bf16 v[6:9], v[124:127], v[136:139], v[6:9]
	v_mfma_f32_16x16x32_bf16 v[10:13], v[128:131], v[136:139], v[10:13]
	v_mfma_f32_16x16x32_bf16 v[14:17], v[132:135], v[136:139], v[14:17]
	v_mfma_f32_16x16x32_bf16 v[18:21], v[120:123], v[152:155], v[18:21]
	v_mfma_f32_16x16x32_bf16 v[22:25], v[124:127], v[152:155], v[22:25]
	v_mfma_f32_16x16x32_bf16 v[26:29], v[128:131], v[152:155], v[26:29]
	v_mfma_f32_16x16x32_bf16 v[30:33], v[132:135], v[152:155], v[30:33]
	v_mfma_f32_16x16x32_bf16 v[34:37], v[120:123], v[156:159], v[34:37]
	v_mfma_f32_16x16x32_bf16 v[38:41], v[124:127], v[156:159], v[38:41]
	v_mfma_f32_16x16x32_bf16 v[42:45], v[128:131], v[156:159], v[42:45]
	v_mfma_f32_16x16x32_bf16 v[46:49], v[132:135], v[156:159], v[46:49]
	v_mfma_f32_16x16x32_bf16 v[50:53], v[120:123], v[160:163], v[50:53]
	v_mfma_f32_16x16x32_bf16 v[54:57], v[124:127], v[160:163], v[54:57]
	v_mfma_f32_16x16x32_bf16 v[58:61], v[128:131], v[160:163], v[58:61]
	v_mfma_f32_16x16x32_bf16 v[62:65], v[132:135], v[160:163], v[62:65]
	global_load_dwordx4 v[120:123], v[78:79], off offset:256
	global_load_dwordx4 v[124:127], v[86:87], off offset:256
	global_load_dwordx4 v[128:131], v[174:175], off offset:256
	global_load_dwordx4 v[132:135], v[172:173], off offset:256
	global_load_dwordx4 v[136:139], v[90:91], off offset:256
	global_load_dwordx4 v[152:155], v[94:95], off offset:256
	global_load_dwordx4 v[156:159], v[96:97], off offset:256
	global_load_dwordx4 v[160:163], v[98:99], off offset:256
	s_waitcnt vmcnt(16)
	v_mfma_f32_16x16x32_bf16 v[2:5], v[164:167], v[212:215], v[2:5]
	v_mfma_f32_16x16x32_bf16 v[6:9], v[200:203], v[212:215], v[6:9]
	v_mfma_f32_16x16x32_bf16 v[10:13], v[204:207], v[212:215], v[10:13]
	v_mfma_f32_16x16x32_bf16 v[14:17], v[208:211], v[212:215], v[14:17]
	v_mfma_f32_16x16x32_bf16 v[18:21], v[164:167], v[216:219], v[18:21]
	v_mfma_f32_16x16x32_bf16 v[22:25], v[200:203], v[216:219], v[22:25]
	v_mfma_f32_16x16x32_bf16 v[26:29], v[204:207], v[216:219], v[26:29]
	v_mfma_f32_16x16x32_bf16 v[30:33], v[208:211], v[216:219], v[30:33]
	v_mfma_f32_16x16x32_bf16 v[34:37], v[164:167], v[220:223], v[34:37]
	v_mfma_f32_16x16x32_bf16 v[38:41], v[200:203], v[220:223], v[38:41]
	v_mfma_f32_16x16x32_bf16 v[42:45], v[204:207], v[220:223], v[42:45]
	v_mfma_f32_16x16x32_bf16 v[46:49], v[208:211], v[220:223], v[46:49]
	v_mfma_f32_16x16x32_bf16 v[50:53], v[164:167], v[224:227], v[50:53]
	v_mfma_f32_16x16x32_bf16 v[54:57], v[200:203], v[224:227], v[54:57]
	v_mfma_f32_16x16x32_bf16 v[58:61], v[204:207], v[224:227], v[58:61]
	v_mfma_f32_16x16x32_bf16 v[62:65], v[208:211], v[224:227], v[62:65]
	global_load_dwordx4 v[164:167], v[78:79], off offset:320
	global_load_dwordx4 v[200:203], v[86:87], off offset:320
	global_load_dwordx4 v[204:207], v[174:175], off offset:320
	global_load_dwordx4 v[208:211], v[172:173], off offset:320
	global_load_dwordx4 v[212:215], v[90:91], off offset:320
	global_load_dwordx4 v[216:219], v[94:95], off offset:320
	global_load_dwordx4 v[220:223], v[96:97], off offset:320
	global_load_dwordx4 v[224:227], v[98:99], off offset:320
	s_waitcnt vmcnt(16)
; template <int CH>
; DEV void cg_chunk(f32x4 (&acc)[4][4], const bf16_t* ap, const bf16_t* bp, const int (&brow)[4], int K) {
;     bf16x8 a[CH][4], b[CH][4];
; #pragma unroll
;     for (int c = 0; c < CH; ++c)
; #pragma unroll
;         for (int i = 0; i < 4; ++i) { a[c][i] = *(const bf16x8*)(ap + (size_t)(16 * i) * K + 32 * c); b[c][i] = *(const bf16x8*)(bp + (size_t)brow[i] * K + 32 * c); }
; #pragma unroll
;     for (int c = 0; c < CH; ++c)
; #pragma unroll
;         for (int mi = 0; mi < 4; ++mi)
; #pragma unroll
;             for (int ni = 0; ni < 4; ++ni) acc[mi][ni] = __builtin_amdgcn_mfma_f32_16x16x32_bf16(b[c][ni], a[c][mi], acc[mi][ni], 0, 0, 0);
; }
	v_mfma_f32_16x16x32_bf16 v[2:5], v[66:69], v[104:107], v[2:5]
	v_mfma_f32_16x16x32_bf16 v[6:9], v[70:73], v[104:107], v[6:9]
	v_mfma_f32_16x16x32_bf16 v[10:13], v[80:83], v[104:107], v[10:13]
	v_mfma_f32_16x16x32_bf16 v[14:17], v[100:103], v[104:107], v[14:17]
	v_mfma_f32_16x16x32_bf16 v[18:21], v[66:69], v[108:111], v[18:21]
	v_mfma_f32_16x16x32_bf16 v[22:25], v[70:73], v[108:111], v[22:25]
	v_mfma_f32_16x16x32_bf16 v[26:29], v[80:83], v[108:111], v[26:29]
	v_mfma_f32_16x16x32_bf16 v[30:33], v[100:103], v[108:111], v[30:33]
	v_mfma_f32_16x16x32_bf16 v[34:37], v[66:69], v[112:115], v[34:37]
	v_mfma_f32_16x16x32_bf16 v[38:41], v[70:73], v[112:115], v[38:41]
	v_mfma_f32_16x16x32_bf16 v[42:45], v[80:83], v[112:115], v[42:45]
	v_mfma_f32_16x16x32_bf16 v[46:49], v[100:103], v[112:115], v[46:49]
	v_mfma_f32_16x16x32_bf16 v[50:53], v[66:69], v[116:119], v[50:53]
	v_mfma_f32_16x16x32_bf16 v[54:57], v[70:73], v[116:119], v[54:57]
	v_mfma_f32_16x16x32_bf16 v[58:61], v[80:83], v[116:119], v[58:61]
	v_mfma_f32_16x16x32_bf16 v[62:65], v[100:103], v[116:119], v[62:65]
	global_load_dwordx4 v[66:69], v[78:79], off offset:384
	global_load_dwordx4 v[70:73], v[86:87], off offset:384
	global_load_dwordx4 v[80:83], v[174:175], off offset:384
	global_load_dwordx4 v[100:103], v[172:173], off offset:384
	global_load_dwordx4 v[104:107], v[90:91], off offset:384
	global_load_dwordx4 v[108:111], v[94:95], off offset:384
	global_load_dwordx4 v[112:115], v[96:97], off offset:384
	global_load_dwordx4 v[116:119], v[98:99], off offset:384
	s_waitcnt vmcnt(16)
	v_mfma_f32_16x16x32_bf16 v[2:5], v[120:123], v[136:139], v[2:5]
	v_mfma_f32_16x16x32_bf16 v[6:9], v[124:127], v[136:139], v[6:9]
	v_mfma_f32_16x16x32_bf16 v[10:13], v[128:131], v[136:139], v[10:13]
	v_mfma_f32_16x16x32_bf16 v[14:17], v[132:135], v[136:139], v[14:17]
	v_mfma_f32_16x16x32_bf16 v[18:21], v[120:123], v[152:155], v[18:21]
	v_mfma_f32_16x16x32_bf16 v[22:25], v[124:127], v[152:155], v[22:25]
	v_mfma_f32_16x16x32_bf16 v[26:29], v[128:131], v[152:155], v[26:29]
	v_mfma_f32_16x16x32_bf16 v[30:33], v[132:135], v[152:155], v[30:33]
	v_mfma_f32_16x16x32_bf16 v[34:37], v[120:123], v[156:159], v[34:37]
	v_mfma_f32_16x16x32_bf16 v[38:41], v[124:127], v[156:159], v[38:41]
	v_mfma_f32_16x16x32_bf16 v[42:45], v[128:131], v[156:159], v[42:45]
	v_mfma_f32_16x16x32_bf16 v[46:49], v[132:135], v[156:159], v[46:49]
	v_mfma_f32_16x16x32_bf16 v[50:53], v[120:123], v[160:163], v[50:53]
	v_mfma_f32_16x16x32_bf16 v[54:57], v[124:127], v[160:163], v[54:57]
	v_mfma_f32_16x16x32_bf16 v[58:61], v[128:131], v[160:163], v[58:61]
	v_mfma_f32_16x16x32_bf16 v[62:65], v[132:135], v[160:163], v[62:65]
	global_load_dwordx4 v[120:123], v[78:79], off offset:448
	global_load_dwordx4 v[124:127], v[86:87], off offset:448
	global_load_dwordx4 v[128:131], v[174:175], off offset:448
	global_load_dwordx4 v[132:135], v[172:173], off offset:448
	global_load_dwordx4 v[136:139], v[90:91], off offset:448
	global_load_dwordx4 v[152:155], v[94:95], off offset:448
	global_load_dwordx4 v[156:159], v[96:97], off offset:448
	global_load_dwordx4 v[160:163], v[98:99], off offset:448
	s_waitcnt vmcnt(16)
	v_mfma_f32_16x16x32_bf16 v[2:5], v[164:167], v[212:215], v[2:5]
	v_mfma_f32_16x16x32_bf16 v[6:9], v[200:203], v[212:215], v[6:9]
	v_mfma_f32_16x16x32_bf16 v[10:13], v[204:207], v[212:215], v[10:13]
	v_mfma_f32_16x16x32_bf16 v[14:17], v[208:211], v[212:215], v[14:17]
	v_mfma_f32_16x16x32_bf16 v[18:21], v[164:167], v[216:219], v[18:21]
	v_mfma_f32_16x16x32_bf16 v[22:25], v[200:203], v[216:219], v[22:25]
	v_mfma_f32_16x16x32_bf16 v[26:29], v[204:207], v[216:219], v[26:29]
	v_mfma_f32_16x16x32_bf16 v[30:33], v[208:211], v[216:219], v[30:33]
	v_mfma_f32_16x16x32_bf16 v[34:37], v[164:167], v[220:223], v[34:37]
	v_mfma_f32_16x16x32_bf16 v[38:41], v[200:203], v[220:223], v[38:41]
	v_mfma_f32_16x16x32_bf16 v[42:45], v[204:207], v[220:223], v[42:45]
	v_mfma_f32_16x16x32_bf16 v[46:49], v[208:211], v[220:223], v[46:49]
	v_mfma_f32_16x16x32_bf16 v[50:53], v[164:167], v[224:227], v[50:53]
	v_mfma_f32_16x16x32_bf16 v[54:57], v[200:203], v[224:227], v[54:57]
	v_mfma_f32_16x16x32_bf16 v[58:61], v[204:207], v[224:227], v[58:61]
	v_mfma_f32_16x16x32_bf16 v[62:65], v[208:211], v[224:227], v[62:65]
	global_load_dwordx4 v[164:167], v[78:79], off offset:512
	global_load_dwordx4 v[200:203], v[86:87], off offset:512
	global_load_dwordx4 v[204:207], v[174:175], off offset:512
	global_load_dwordx4 v[208:211], v[172:173], off offset:512
	global_load_dwordx4 v[212:215], v[90:91], off offset:512
	global_load_dwordx4 v[216:219], v[94:95], off offset:512
	global_load_dwordx4 v[220:223], v[96:97], off offset:512
	global_load_dwordx4 v[224:227], v[98:99], off offset:512
	s_waitcnt vmcnt(16)
	v_mfma_f32_16x16x32_bf16 v[2:5], v[66:69], v[104:107], v[2:5]
	v_mfma_f32_16x16x32_bf16 v[6:9], v[70:73], v[104:107], v[6:9]
	v_mfma_f32_16x16x32_bf16 v[10:13], v[80:83], v[104:107], v[10:13]
	v_mfma_f32_16x16x32_bf16 v[14:17], v[100:103], v[104:107], v[14:17]
	v_mfma_f32_16x16x32_bf16 v[18:21], v[66:69], v[108:111], v[18:21]
	v_mfma_f32_16x16x32_bf16 v[22:25], v[70:73], v[108:111], v[22:25]
	v_mfma_f32_16x16x32_bf16 v[26:29], v[80:83], v[108:111], v[26:29]
	v_mfma_f32_16x16x32_bf16 v[30:33], v[100:103], v[108:111], v[30:33]
	v_mfma_f32_16x16x32_bf16 v[34:37], v[66:69], v[112:115], v[34:37]
	v_mfma_f32_16x16x32_bf16 v[38:41], v[70:73], v[112:115], v[38:41]
	v_mfma_f32_16x16x32_bf16 v[42:45], v[80:83], v[112:115], v[42:45]
	v_mfma_f32_16x16x32_bf16 v[46:49], v[100:103], v[112:115], v[46:49]
	v_mfma_f32_16x16x32_bf16 v[50:53], v[66:69], v[116:119], v[50:53]
	v_mfma_f32_16x16x32_bf16 v[54:57], v[70:73], v[116:119], v[54:57]
	v_mfma_f32_16x16x32_bf16 v[58:61], v[80:83], v[116:119], v[58:61]
	v_mfma_f32_16x16x32_bf16 v[62:65], v[100:103], v[116:119], v[62:65]
	global_load_dwordx4 v[66:69], v[78:79], off offset:576
	global_load_dwordx4 v[70:73], v[86:87], off offset:576
	global_load_dwordx4 v[80:83], v[174:175], off offset:576
	global_load_dwordx4 v[100:103], v[172:173], off offset:576
	global_load_dwordx4 v[104:107], v[90:91], off offset:576
	global_load_dwordx4 v[108:111], v[94:95], off offset:576
	global_load_dwordx4 v[112:115], v[96:97], off offset:576
	global_load_dwordx4 v[116:119], v[98:99], off offset:576
	s_waitcnt vmcnt(16)
; #define LAS __attribute__((address_space(3)))
; template <int CH>
; DEV void cg_chunk(f32x4 (&acc)[4][4], const bf16_t* ap, const bf16_t* bp, const int (&brow)[4], int K) {
;     bf16x8 a[CH][4], b[CH][4];
; #pragma unroll
;     for (int c = 0; c < CH; ++c)
; #pragma unroll
;         for (int i = 0; i < 4; ++i) { a[c][i] = *(const bf16x8*)(ap + (size_t)(16 * i) * K + 32 * c); b[c][i] = *(const bf16x8*)(bp + (size_t)brow[i] * K + 32 * c); }
; #pragma unroll
;     for (int c = 0; c < CH; ++c)
; #pragma unroll
;         for (int mi = 0; mi < 4; ++mi)
; #pragma unroll
;             for (int ni = 0; ni < 4; ++ni) acc[mi][ni] = __builtin_amdgcn_mfma_f32_16x16x32_bf16(b[c][ni], a[c][mi], acc[mi][ni], 0, 0, 0);
; }
; template <int MODE>
; DEV void cgemm_tile(const Fr& F, const bf16_t* A, const bf16_t* Bt, int K, int rb, int cb, bf16_t* O, int ldc) {
;     LAS float* part = (LAS float*)F.lds;
;     const int w = F.wave, fr = F.lane & 15, fq = F.lane >> 4;
;     const int arow0 = (rb >> 2) * RPB + (rb & 3) * 64;
;     int brow[4];
; #pragma unroll
;     for (int ni = 0; ni < 4; ++ni) {
;         if (MODE == 0) brow[ni] = cb * 64 + ni * 16;
;         else { const int j = cb * 32 + (ni & 1) * 16; brow[ni] = (j >> 7) * 256 + (ni >> 1) * 128 + (j & 127); }
;     }
;     const int kslice = K >> 3, steps = kslice >> 5;
;     const bf16_t* ap = A + (size_t)(arow0 + fr) * K + w * kslice + 8 * fq;
;     const bf16_t* bp = Bt + (size_t)fr * K + w * kslice + 8 * fq;
;     f32x4 acc[4][4];
; #pragma unroll
;     for (int mi = 0; mi < 4; ++mi)
; #pragma unroll
;         for (int ni = 0; ni < 4; ++ni) acc[mi][ni] = (f32x4){0.f, 0.f, 0.f, 0.f};
;     int s = 0;
;     for (; s + 4 <= steps; s += 4) cg_chunk<4>(acc, ap + s * 32, bp + s * 32, brow, K);
;     if (steps - s == 3) cg_chunk<3>(acc, ap + s * 32, bp + s * 32, brow, K);
;     else if (steps - s == 2) cg_chunk<2>(acc, ap + s * 32, bp + s * 32, brow, K);
;     else if (steps - s == 1) cg_chunk<1>(acc, ap + s * 32, bp + s * 32, brow, K);
; #pragma unroll
;     for (int mi = 0; mi < 4; ++mi)
; #pragma unroll
;         for (int ni = 0; ni < 4; ++ni) *(LAS f32x4*)(part + (w * 64 + 16 * mi + fr) * 64 + ((16 * ni + 4 * fq) ^ (fr << 2))) = acc[mi][ni];
;     __syncthreads();
	v_mfma_f32_16x16x32_bf16 v[2:5], v[120:123], v[136:139], v[2:5]
	v_mfma_f32_16x16x32_bf16 v[6:9], v[124:127], v[136:139], v[6:9]
	v_mfma_f32_16x16x32_bf16 v[10:13], v[128:131], v[136:139], v[10:13]
	v_mfma_f32_16x16x32_bf16 v[14:17], v[132:135], v[136:139], v[14:17]
	v_mfma_f32_16x16x32_bf16 v[18:21], v[120:123], v[152:155], v[18:21]
	v_mfma_f32_16x16x32_bf16 v[22:25], v[124:127], v[152:155], v[22:25]
	v_mfma_f32_16x16x32_bf16 v[26:29], v[128:131], v[152:155], v[26:29]
	v_mfma_f32_16x16x32_bf16 v[30:33], v[132:135], v[152:155], v[30:33]
	v_mfma_f32_16x16x32_bf16 v[34:37], v[120:123], v[156:159], v[34:37]
	v_mfma_f32_16x16x32_bf16 v[38:41], v[124:127], v[156:159], v[38:41]
	v_mfma_f32_16x16x32_bf16 v[42:45], v[128:131], v[156:159], v[42:45]
	v_mfma_f32_16x16x32_bf16 v[46:49], v[132:135], v[156:159], v[46:49]
	v_mfma_f32_16x16x32_bf16 v[50:53], v[120:123], v[160:163], v[50:53]
	v_mfma_f32_16x16x32_bf16 v[54:57], v[124:127], v[160:163], v[54:57]
	v_mfma_f32_16x16x32_bf16 v[58:61], v[128:131], v[160:163], v[58:61]
	v_mfma_f32_16x16x32_bf16 v[62:65], v[132:135], v[160:163], v[62:65]
	global_load_dwordx4 v[120:123], v[78:79], off offset:640
	global_load_dwordx4 v[124:127], v[86:87], off offset:640
	global_load_dwordx4 v[128:131], v[174:175], off offset:640
	global_load_dwordx4 v[132:135], v[172:173], off offset:640
	global_load_dwordx4 v[136:139], v[90:91], off offset:640
	global_load_dwordx4 v[152:155], v[94:95], off offset:640
	global_load_dwordx4 v[156:159], v[96:97], off offset:640
	global_load_dwordx4 v[160:163], v[98:99], off offset:640
	s_waitcnt vmcnt(16)
	v_mfma_f32_16x16x32_bf16 v[2:5], v[164:167], v[212:215], v[2:5]
	v_mfma_f32_16x16x32_bf16 v[6:9], v[200:203], v[212:215], v[6:9]
	v_mfma_f32_16x16x32_bf16 v[10:13], v[204:207], v[212:215], v[10:13]
	v_mfma_f32_16x16x32_bf16 v[14:17], v[208:211], v[212:215], v[14:17]
	v_mfma_f32_16x16x32_bf16 v[18:21], v[164:167], v[216:219], v[18:21]
	v_mfma_f32_16x16x32_bf16 v[22:25], v[200:203], v[216:219], v[22:25]
	v_mfma_f32_16x16x32_bf16 v[26:29], v[204:207], v[216:219], v[26:29]
	v_mfma_f32_16x16x32_bf16 v[30:33], v[208:211], v[216:219], v[30:33]
	v_mfma_f32_16x16x32_bf16 v[34:37], v[164:167], v[220:223], v[34:37]
	v_mfma_f32_16x16x32_bf16 v[38:41], v[200:203], v[220:223], v[38:41]
	v_mfma_f32_16x16x32_bf16 v[42:45], v[204:207], v[220:223], v[42:45]
	v_mfma_f32_16x16x32_bf16 v[46:49], v[208:211], v[220:223], v[46:49]
	v_mfma_f32_16x16x32_bf16 v[50:53], v[164:167], v[224:227], v[50:53]
	v_mfma_f32_16x16x32_bf16 v[54:57], v[200:203], v[224:227], v[54:57]
	v_mfma_f32_16x16x32_bf16 v[58:61], v[204:207], v[224:227], v[58:61]
	v_mfma_f32_16x16x32_bf16 v[62:65], v[208:211], v[224:227], v[62:65]
	s_waitcnt vmcnt(8)
	v_mfma_f32_16x16x32_bf16 v[2:5], v[66:69], v[104:107], v[2:5]
	v_mfma_f32_16x16x32_bf16 v[6:9], v[70:73], v[104:107], v[6:9]
	v_mfma_f32_16x16x32_bf16 v[10:13], v[80:83], v[104:107], v[10:13]
	v_mfma_f32_16x16x32_bf16 v[14:17], v[100:103], v[104:107], v[14:17]
	v_mfma_f32_16x16x32_bf16 v[18:21], v[66:69], v[108:111], v[18:21]
	v_mfma_f32_16x16x32_bf16 v[22:25], v[70:73], v[108:111], v[22:25]
	v_mfma_f32_16x16x32_bf16 v[26:29], v[80:83], v[108:111], v[26:29]
	v_mfma_f32_16x16x32_bf16 v[30:33], v[100:103], v[108:111], v[30:33]
	v_mfma_f32_16x16x32_bf16 v[34:37], v[66:69], v[112:115], v[34:37]
	v_mfma_f32_16x16x32_bf16 v[38:41], v[70:73], v[112:115], v[38:41]
	v_mfma_f32_16x16x32_bf16 v[42:45], v[80:83], v[112:115], v[42:45]
	v_mfma_f32_16x16x32_bf16 v[46:49], v[100:103], v[112:115], v[46:49]
	v_mfma_f32_16x16x32_bf16 v[50:53], v[66:69], v[116:119], v[50:53]
	v_mfma_f32_16x16x32_bf16 v[54:57], v[70:73], v[116:119], v[54:57]
	v_mfma_f32_16x16x32_bf16 v[58:61], v[80:83], v[116:119], v[58:61]
	v_mfma_f32_16x16x32_bf16 v[62:65], v[100:103], v[116:119], v[62:65]
	s_waitcnt vmcnt(0)
	v_mfma_f32_16x16x32_bf16 v[2:5], v[120:123], v[136:139], v[2:5]
	v_mfma_f32_16x16x32_bf16 v[6:9], v[124:127], v[136:139], v[6:9]
	v_mfma_f32_16x16x32_bf16 v[10:13], v[128:131], v[136:139], v[10:13]
	v_mfma_f32_16x16x32_bf16 v[14:17], v[132:135], v[136:139], v[14:17]
	v_mfma_f32_16x16x32_bf16 v[18:21], v[120:123], v[152:155], v[18:21]
	v_mfma_f32_16x16x32_bf16 v[22:25], v[124:127], v[152:155], v[22:25]
	v_mfma_f32_16x16x32_bf16 v[26:29], v[128:131], v[152:155], v[26:29]
	v_mfma_f32_16x16x32_bf16 v[30:33], v[132:135], v[152:155], v[30:33]
	v_mfma_f32_16x16x32_bf16 v[34:37], v[120:123], v[156:159], v[34:37]
	v_mfma_f32_16x16x32_bf16 v[38:41], v[124:127], v[156:159], v[38:41]
	v_mfma_f32_16x16x32_bf16 v[42:45], v[128:131], v[156:159], v[42:45]
	v_mfma_f32_16x16x32_bf16 v[46:49], v[132:135], v[156:159], v[46:49]
	v_mfma_f32_16x16x32_bf16 v[50:53], v[120:123], v[160:163], v[50:53]
	v_mfma_f32_16x16x32_bf16 v[54:57], v[124:127], v[160:163], v[54:57]
	v_mfma_f32_16x16x32_bf16 v[58:61], v[128:131], v[160:163], v[58:61]
	v_mfma_f32_16x16x32_bf16 v[62:65], v[132:135], v[160:163], v[62:65]
	ds_write_b128 v176, v[2:5]
	ds_write_b128 v177, v[6:9]
	ds_write_b128 v178, v[10:13]
	ds_write_b128 v179, v[14:17]
	ds_write_b128 v176, v[18:21] offset:4096
	ds_write_b128 v177, v[22:25] offset:4096
	ds_write_b128 v178, v[26:29] offset:4096
	ds_write_b128 v179, v[30:33] offset:4096
	ds_write_b128 v176, v[34:37] offset:8192
	ds_write_b128 v177, v[38:41] offset:8192
	ds_write_b128 v178, v[42:45] offset:8192
	ds_write_b128 v179, v[46:49] offset:8192
	ds_write_b128 v176, v[50:53] offset:12288
	ds_write_b128 v177, v[54:57] offset:12288
	ds_write_b128 v178, v[58:61] offset:12288
	ds_write_b128 v179, v[62:65] offset:12288
	s_waitcnt lgkmcnt(0)
	s_barrier
; #define LAS __attribute__((address_space(3)))
; DEV unsigned pk2(float lo, float hi) { unsigned r; asm("v_cvt_pk_bf16_f32 %0, %1, %2" : "=v"(r) : "v"(lo), "v"(hi)); return r; }
; DEV float fsilu(float x) { return x * fsigmoid(x); }
; template <int MODE>
; DEV void cgemm_tile(const Fr& F, const bf16_t* A, const bf16_t* Bt, int K, int rb, int cb, bf16_t* O, int ldc) {
;     ...
;     { const int row = F.tid >> 3, c8 = (F.tid & 7) * 8, sw = (row & 15) << 2;
;       if (MODE == 0) {
;           f32x4 s0 = (f32x4){0.f, 0.f, 0.f, 0.f}, s1 = s0;
; #pragma unroll
;           for (int ww = 0; ww < 8; ++ww) { s0 += *(const LAS f32x4*)(part + (ww * 64 + row) * 64 + (c8 ^ sw)); s1 += *(const LAS f32x4*)(part + (ww * 64 + row) * 64 + ((c8 + 4) ^ sw)); }
;           u32x4 o; o.x = pk2(s0[0], s0[1]); o.y = pk2(s0[2], s0[3]); o.z = pk2(s1[0], s1[1]); o.w = pk2(s1[2], s1[3]);
;           *(u32x4*)(O + (size_t)(arow0 + row) * ldc + cb * 64 + c8) = o;
;       } else if (c8 < 32) {
;           f32x4 g0 = (f32x4){0.f, 0.f, 0.f, 0.f}, g1 = g0, u0 = g0, u1 = g0;
; #pragma unroll
;           for (int ww = 0; ww < 8; ++ww) { const LAS float* pr = part + (ww * 64 + row) * 64;
;               g0 += *(const LAS f32x4*)(pr + (c8 ^ sw)); g1 += *(const LAS f32x4*)(pr + ((c8 + 4) ^ sw)); u0 += *(const LAS f32x4*)(pr + ((c8 + 32) ^ sw)); u1 += *(const LAS f32x4*)(pr + ((c8 + 36) ^ sw)); }
;           float o[8];
; #pragma unroll
;           for (int j = 0; j < 4; ++j) { o[j] = fsilu(g0[j]) * u0[j]; o[4 + j] = fsilu(g1[j]) * u1[j]; }
;           u32x4 ov; ov.x = pk2(o[0], o[1]); ov.y = pk2(o[2], o[3]); ov.z = pk2(o[4], o[5]); ov.w = pk2(o[6], o[7]);
;           *(u32x4*)(O + (size_t)(arow0 + row) * ldc + cb * 32 + c8) = ov;
;       } }
;     __syncthreads();
	ds_read_b128 v[2:5], v180
	ds_read_b128 v[6:9], v180 offset:16384
	ds_read_b128 v[10:13], v181
	ds_read_b128 v[14:17], v181 offset:16384
	ds_read_b128 v[18:21], v180 offset:32768
	ds_read_b128 v[22:25], v180 offset:49152
	ds_read_b128 v[26:29], v181 offset:32768
	ds_read_b128 v[30:33], v181 offset:49152
	ds_read_b128 v[34:37], v182
	ds_read_b128 v[38:41], v183
	ds_read_b128 v[42:45], v184
	ds_read_b128 v[46:49], v185
	ds_read_b128 v[50:53], v186
	ds_read_b128 v[54:57], v187
	ds_read_b128 v[58:61], v198
	ds_read_b128 v[62:65], v199
	s_waitcnt lgkmcnt(14)
	v_pk_add_f32 v[4:5], v[4:5], 0 op_sel_hi:[1,0]
	v_pk_add_f32 v[2:3], v[2:3], 0 op_sel_hi:[1,0]
	s_waitcnt lgkmcnt(13)
	v_pk_add_f32 v[12:13], v[12:13], 0 op_sel_hi:[1,0]
	v_pk_add_f32 v[10:11], v[10:11], 0 op_sel_hi:[1,0]
	v_pk_add_f32 v[4:5], v[4:5], v[8:9]
	v_pk_add_f32 v[2:3], v[2:3], v[6:7]
	s_waitcnt lgkmcnt(12)
	v_pk_add_f32 v[6:7], v[12:13], v[16:17]
	v_pk_add_f32 v[8:9], v[10:11], v[14:15]
	s_waitcnt lgkmcnt(11)
	v_pk_add_f32 v[4:5], v[4:5], v[20:21]
	v_pk_add_f32 v[2:3], v[2:3], v[18:19]
	s_waitcnt lgkmcnt(9)
	v_pk_add_f32 v[6:7], v[6:7], v[28:29]
	v_pk_add_f32 v[8:9], v[8:9], v[26:27]
	v_pk_add_f32 v[4:5], v[4:5], v[24:25]
	v_pk_add_f32 v[2:3], v[2:3], v[22:23]
	s_waitcnt lgkmcnt(8)
	v_pk_add_f32 v[6:7], v[6:7], v[32:33]
	v_pk_add_f32 v[8:9], v[8:9], v[30:31]
	s_waitcnt lgkmcnt(7)
	v_pk_add_f32 v[4:5], v[4:5], v[36:37]
	v_pk_add_f32 v[2:3], v[2:3], v[34:35]
	s_waitcnt lgkmcnt(6)
	v_pk_add_f32 v[6:7], v[6:7], v[40:41]
	v_pk_add_f32 v[8:9], v[8:9], v[38:39]
	s_waitcnt lgkmcnt(5)
	v_pk_add_f32 v[4:5], v[4:5], v[44:45]
	v_pk_add_f32 v[2:3], v[2:3], v[42:43]
	v_lshl_add_u64 v[70:71], s[0:1], 1, v[170:171]
	s_addk_i32 s0, 0x800
	s_waitcnt lgkmcnt(4)
	v_pk_add_f32 v[6:7], v[6:7], v[48:49]
	v_pk_add_f32 v[8:9], v[8:9], v[46:47]
	s_waitcnt lgkmcnt(3)
	v_pk_add_f32 v[4:5], v[4:5], v[52:53]
	v_pk_add_f32 v[2:3], v[2:3], v[50:51]
	s_cmpk_gt_i32 s2, 0xffef
	s_waitcnt lgkmcnt(2)
	v_pk_add_f32 v[6:7], v[6:7], v[56:57]
	v_pk_add_f32 v[8:9], v[8:9], v[54:55]
	s_waitcnt lgkmcnt(1)
	v_pk_add_f32 v[4:5], v[4:5], v[60:61]
	v_pk_add_f32 v[2:3], v[2:3], v[58:59]
	s_waitcnt lgkmcnt(0)
	v_pk_add_f32 v[6:7], v[6:7], v[64:65]
	v_pk_add_f32 v[8:9], v[8:9], v[62:63]
	v_cvt_pk_bf16_f32 v2, v2, v3
	v_cvt_pk_bf16_f32 v3, v4, v5
	v_cvt_pk_bf16_f32 v5, v6, v7
	s_nop 0
	v_cvt_pk_bf16_f32 v4, v8, v9
	global_store_dwordx4 v[70:71], v[2:5], off
	s_barrier
	s_cbranch_scc0 .LBB0_1385
